# ssd chunk loop: load wait ladder made store-aware (vmcnt 12..8 instead of 4..0; the 8 Y stores are younger than the loads), on top of v055
# baseline (speedup 1.0000x reference)
; #define LAS __attribute__((address_space(3)))
; __device__ __forceinline__ unsigned short bfraw(const v4u& v, int i) { const unsigned u = (i < 2) ? v.x : (i < 4) ? v.y : (i < 6) ? v.z : v.w; return (unsigned short)((i & 1) ? (u >> 16) : (u & 0xffffu)); }
; __device__ __forceinline__ void ssd_scan_fast(KArgs a, int idx, LAS unsigned char* lds, int tid, int lane, int wave) {
;     ...
;     const int fr = lane & 15, fq = lane >> 4, ss = tid & 63, sc = tid >> 6, tl = wave >> 1, wh = wave & 1;
;     { unsigned z = 0u; asm volatile("" : "+v"(z)); for (int i = tid; i < 17408 / 16; i += NTHR) *(LAS v4u*)(lds + SS_HB + i * 16) = (v4u){z, z, z, z}; }
;     f32x4 hacc[4];
; #pragma unroll
;     for (int j = 0; j < 4; ++j) hacc[j] = (f32x4){0.f, 0.f, 0.f, 0.f};
;     ...
;     for (int ch = 0; ch < RJ / 64; ++ch) {
;         *(LAS v4u*)(Cm + ss * 136 + sc * 8) = pc0; *(LAS v4u*)(Cm + ss * 136 + (sc + 8) * 8) = pc1;
;         *(LAS v4u*)(Bm + ss * 136 + sc * 8) = pb0; *(LAS v4u*)(Bm + ss * 136 + (sc + 8) * 8) = pb1;
; #pragma unroll
;         for (int i = 0; i < 8; ++i) XT[(sc * 8 + i) * 72 + ss] = bfraw(px, i);
;         if (tid < 64) { float x = pa;
;             x += __int_as_float(__builtin_amdgcn_update_dpp(0, __float_as_int(x), 0x111, 0xf, 0xf, false)); x += __int_as_float(__builtin_amdgcn_update_dpp(0, __float_as_int(x), 0x112, 0xf, 0xf, false));
;             x += __int_as_float(__builtin_amdgcn_update_dpp(0, __float_as_int(x), 0x114, 0xf, 0xf, false)); x += __int_as_float(__builtin_amdgcn_update_dpp(0, __float_as_int(x), 0x118, 0xf, 0xf, false));
;             x += __int_as_float(__builtin_amdgcn_update_dpp(0, __float_as_int(x), 0x142, 0xa, 0xf, false)); x += __int_as_float(__builtin_amdgcn_update_dpp(0, __float_as_int(x), 0x143, 0xc, 0xf, false));
;             CS[tid] = x; DTV[tid] = pdt; }
.LBB0_908:
	s_or_b64 exec, exec, s[6:7]
	s_and_b64 s[6:7], s[36:37], exec
	s_cselect_b32 s6, 0, 0x1b00000
	s_add_u32 s6, s2, s6
	s_movk_i32 s29, 0x110
	s_movk_i32 s28, 0x90
	s_addc_u32 s7, s3, 0
	s_ashr_i32 s20, s8, 1
	v_mad_u32_u24 v8, v104, s29, 0
	s_movk_i32 s18, 0xfef2
	v_mul_lo_u32 v6, v4, s28
	v_and_b32_e32 v7, 15, v86
	v_mad_i32_i24 v10, v104, s18, v8
	v_lshlrev_b32_e32 v4, 2, v104
	v_readlane_b32 s31, v253, 57
	v_readlane_b32 s33, v253, 58
	s_lshl_b32 s18, s20, 4
	v_ashrrev_i32_e32 v0, 4, v86
	v_add_u32_e32 v107, s31, v4
	v_add_u32_e32 v108, s33, v4
	v_or_b32_e32 v4, s18, v7
	s_and_b32 s21, s8, 1
	v_mul_lo_u32 v5, v4, s29
	v_lshl_add_u32 v89, v0, 2, s18
	s_lshl_b32 s18, s20, 6
	v_add_u32_e32 v112, 0, v5
	s_lshl_b32 s25, s21, 1
	v_lshlrev_b32_e32 v0, 7, v4
	s_add_i32 s26, 0, 0x11800
	s_add_i32 s18, s33, s18
	s_lshl_b32 s27, s9, 2
	v_and_b32_e32 v113, -16, v86
	v_sub_u32_e32 v0, v112, v0
	s_add_u32 s6, s6, s27
	v_add_u32_e32 v91, v0, v113
	s_addc_u32 s7, s7, 0
	v_lshlrev_b32_e32 v0, 2, v7
	s_lshl_b32 s34, s21, 7
	v_add_u32_e32 v114, s26, v113
	v_lshl_add_u64 v[4:5], s[6:7], 0, v[0:1]
	s_lshl_b32 s6, s16, 11
	s_or_b32 s7, s17, 0x2000
	s_add_i32 s26, s26, s34
	s_movk_i32 s16, 0x480
	s_cmp_le_i32 s25, s20
	v_lshlrev_b32_e32 v9, 4, v3
	v_lshl_or_b32 v0, s21, 6, v7
	v_lshl_add_u32 v11, v7, 1, s26
	v_mul_lo_u32 v3, v3, s16
	s_cselect_b64 s[16:17], -1, 0
	v_lshl_or_b32 v7, s21, 5, v7
	s_cmp_lt_i32 s25, s20
	v_lshlrev_b32_e32 v12, 2, v138
	v_or_b32_e32 v13, 1, v89
	v_or_b32_e32 v14, 2, v89
	v_or_b32_e32 v15, 3, v89
	s_cselect_b64 s[20:21], -1, 0
	v_or_b32_e32 v16, 16, v7
	v_lshlrev_b32_e32 v38, 2, v7
	v_lshl_add_u64 v[4:5], v[4:5], 0, s[34:35]
	s_mov_b64 s[26:27], 0x40e00000
	s_lshl_b32 s24, s24, 2
	v_add_u32_e32 v97, 0, v113
	v_add_u32_e32 v110, s33, v12
	v_add_u32_e32 v111, s31, v12
	v_add_u32_e32 v6, 0x2400, v6
	v_mul_u32_u24_e32 v103, 0x110, v7
	v_mul_lo_u32 v12, v89, s28
	v_mul_u32_u24_e32 v0, 0x90, v0
	v_mul_lo_u32 v17, v89, s29
	v_add_u32_e32 v101, s33, v38
	v_add_u32_e32 v102, s31, v38
	v_lshl_add_u32 v38, v7, 1, 0
	v_cmp_le_i32_e64 s[52:53], v7, v89
	v_cmp_le_i32_e64 s[50:51], v7, v13
	v_cmp_le_i32_e64 s[48:49], v7, v14
	v_cmp_le_i32_e64 s[46:47], v7, v15
	v_lshlrev_b32_e32 v39, 2, v16
	v_mul_u32_u24_e32 v7, 0x90, v7
	v_lshl_add_u64 v[70:71], v[4:5], 0, s[26:27]
	v_mul_u32_u24_e32 v4, 0x90, v16
	s_add_u32 s24, s4, s24
	s_mov_b32 s15, 0
	v_lshl_add_u32 v96, v89, 2, s33
	v_lshl_add_u32 v95, v13, 2, s33
	v_lshl_add_u32 v93, v14, 2, s33
	v_lshl_add_u32 v92, v15, 2, s33
	v_mul_u32_u24_e32 v100, 0x110, v16
	v_add_u32_e32 v98, s33, v39
	v_add_u32_e32 v99, s31, v39
	v_cmp_le_i32_e64 s[44:45], v16, v89
	v_cmp_le_i32_e64 s[42:43], v16, v13
	v_cmp_le_i32_e64 s[40:41], v16, v14
	v_cmp_le_i32_e64 s[38:39], v16, v15
	s_addc_u32 s25, s5, 0
	v_sub_u32_e32 v117, 0, v89
	v_sub_u32_e32 v118, 0xffffffc0, v104
	s_lshl_b32 s34, s19, 1
	v_add_u32_e32 v116, v8, v9
	v_add_u32_e32 v109, v10, v3
	v_add_u32_e32 v115, v10, v6
	v_add_u32_e32 v94, v38, v12
	v_add_u32_e32 v90, v97, v7
	v_add_u32_e32 v88, v97, v4
	v_add_u32_e32 v87, v97, v0
	v_add_u32_e32 v0, v11, v17
	s_mov_b32 s19, 0
	s_mov_b32 s26, 0
	v_mov_b32_e32 v3, v2
	v_mov_b32_e32 v4, v2
	v_mov_b32_e32 v5, v2
	v_mov_b32_e32 v6, v2
	v_mov_b32_e32 v7, v2
	v_mov_b32_e32 v8, v2
	v_mov_b32_e32 v9, v2
	v_mov_b32_e32 v10, v2
	v_mov_b32_e32 v11, v2
	v_mov_b32_e32 v12, v2
	v_mov_b32_e32 v13, v2
	v_mov_b32_e32 v14, v2
	v_mov_b32_e32 v15, v2
	v_mov_b32_e32 v16, v2
	v_mov_b32_e32 v17, v2
	s_waitcnt vmcnt(0)
	s_branch .LBB0_910
.LBB0_910:
	s_waitcnt vmcnt(12)
	ds_write_b128 v116, v[30:33]
	s_waitcnt vmcnt(11)
	ds_write_b128 v116, v[34:37] offset:128
	s_waitcnt vmcnt(10)
	ds_write_b128 v116, v[22:25] offset:17408
	s_waitcnt vmcnt(9)
	ds_write_b128 v116, v[18:21] offset:17536
	s_waitcnt vmcnt(8)
	ds_write_b16 v109, v26 offset:53248
	ds_write_b16_d16_hi v109, v26 offset:53392
	ds_write_b16 v109, v27 offset:53536
	ds_write_b16_d16_hi v109, v27 offset:53680
	ds_write_b16 v109, v28 offset:53824
	ds_write_b16_d16_hi v109, v28 offset:53968
	ds_write_b16 v109, v29 offset:54112
	ds_write_b16_d16_hi v109, v29 offset:54256
	s_and_saveexec_b64 s[4:5], s[54:55]
	s_cbranch_execz .LBB0_912
	v_add_f32_dpp v26, v106, v106 row_shr:1 row_mask:0xf bank_mask:0xf bound_ctrl:1
	v_mov_b32_e32 v27, v1
	s_nop 0
	v_add_f32_dpp v26, v26, v26 row_shr:2 row_mask:0xf bank_mask:0xf bound_ctrl:1
	s_nop 1
	v_add_f32_dpp v26, v26, v26 row_shr:4 row_mask:0xf bank_mask:0xf bound_ctrl:1
	s_nop 1
	v_add_f32_dpp v26, v26, v26 row_shr:8 row_mask:0xf bank_mask:0xf bound_ctrl:1
	s_nop 1
	v_mov_b32_dpp v27, v26 row_bcast:15 row_mask:0xa bank_mask:0xf
	v_add_f32_e32 v26, v26, v27
	v_mov_b32_e32 v27, v1
	s_nop 1
	v_mov_b32_dpp v27, v26 row_bcast:31 row_mask:0xc bank_mask:0xf
	v_add_f32_e32 v26, v26, v27
	ds_write_b32 v110, v26
	ds_write_b32 v111, v105
; #define LAS __attribute__((address_space(3)))
; __device__ __forceinline__ bf16 bf1(float x) { return (bf16)(pk2(x, x) & 0xffffu); }
; __device__ __forceinline__ float bfe(const v4u& v, int i) { const unsigned u = (i < 2) ? v.x : (i < 4) ? v.y : (i < 6) ? v.z : v.w; return (i & 1) ? bfhi(u) : bflo(u); }
; __device__ __forceinline__ void ssd_scan_fast(KArgs a, int idx, LAS unsigned char* lds, int tid, int lane, int wave) {
;     ...
;     auto issue = [&](int ch) {
;         const int tok = ssd_tok(b, dir, ch * 64 + ss); const bf16* row = XBC + (size_t)tok * 1792;
;         pc0 = *(const v4u*)(row + 1280 + g * 128 + sc * 8); pc1 = *(const v4u*)(row + 1280 + g * 128 + (sc + 8) * 8);
;         pb0 = *(const v4u*)(row + 768 + g * 128 + sc * 8); pb1 = *(const v4u*)(row + 768 + g * 128 + (sc + 8) * 8);
;         px = *(const v4u*)(row + h * 64 + sc * 8);
;         if (tid < 64) { pdt = DTA[(size_t)tok * 48 + q]; pa = DTA[(size_t)tok * 48 + 24 + q]; }
;     };
;     ...
;         const float cl = CS[63];
;         { const float scl = DTV[ss] * __expf(cl - CS[ss]);
; #pragma unroll
;             for (int i = 0; i < 8; ++i) { BsT[(sc * 8 + i) * 72 + ss] = bf1(bfe(pb0, i) * scl); BsT[((sc + 8) * 8 + i) * 72 + ss] = bf1(bfe(pb1, i) * scl); } }
;         if (ch + 1 < RJ / 64) issue(ch + 1);
;         bf16x8 cf[4];
; #pragma unroll
;         for (int ks = 0; ks < 4; ++ks) cf[ks] = *(const LAS bf16x8*)(Cm + (16 * tl + fr) * 136 + ks * 32 + fq * 8);
; #pragma unroll
;         for (int j = 0; j < 2; ++j) { const int tc = wh * 2 + j; f32x4 acc = (f32x4){0.f, 0.f, 0.f, 0.f};
;             if (tc <= tl) {
; #pragma unroll
;                 for (int ks = 0; ks < 4; ++ks) { const bf16x8 bf = *(const LAS bf16x8*)(Bm + (16 * tc + fr) * 136 + ks * 32 + fq * 8);
;                     acc = __builtin_amdgcn_mfma_f32_16x16x32_bf16(cf[ks], bf, acc, 0, 0, 0); } }
.LBB0_912:
	s_or_b64 exec, exec, s[4:5]
	v_readlane_b32 s4, v253, 59
	s_waitcnt lgkmcnt(0)
	s_barrier
	v_mov_b32_e32 v26, s4
	ds_read_b32 v119, v26
	ds_read_b32 v26, v107
	ds_read_b32 v27, v108
	ds_read_b32 v128, v101
	ds_read_b32 v129, v102
	ds_read_b32 v130, v98
	ds_read_b32 v131, v99
	ds_read_b32 v132, v96
	ds_read_b32 v133, v95
	ds_read_b32 v134, v93
	ds_read_b32 v135, v92
	v_add_u32_e32 v122, v112, v113
	ds_read_b128 v[58:61], v122
	ds_read_b128 v[54:57], v122 offset:64
	ds_read_b128 v[50:53], v122 offset:128
	ds_read_b128 v[46:49], v122 offset:192
	s_cmp_lt_u32 s26, 3
	s_cselect_b64 vcc, -1, 0
	s_and_b64 s[4:5], vcc, exec
	s_movk_i32 s4, 0x8ff
	s_cselect_b32 s4, 0xff, s4
	s_cselect_b32 s5, s7, s6
	s_add_i32 s4, s15, s4
	v_mov_b32_e32 v240, 0
	v_mov_b32_e32 v241, 0
	v_mov_b32_e32 v242, 0
	v_mov_b32_e32 v243, 0
	v_mov_b32_e32 v244, 0
	v_mov_b32_e32 v245, 0
	v_mov_b32_e32 v246, 0
	v_mov_b32_e32 v247, 0
	v_cndmask_b32_e64 v188, 0, 1, s[16:17]
	v_cndmask_b32_e64 v189, 0, 1, s[20:21]
	v_cmp_ne_u32_e64 s[56:57], 1, v188
	v_cmp_ne_u32_e64 s[58:59], 1, v189
	v_add_u32_e32 v42, v97, v103
	v_add_u32_e32 v62, v97, v100
	s_waitcnt lgkmcnt(12)
	v_sub_f32_e32 v27, v119, v27
	v_mul_f32_e32 v27, 0x3fb8aa3b, v27
	v_exp_f32_e32 v27, v27
	s_waitcnt lgkmcnt(4)
	ds_read_b128 v[140:143], v42 offset:17408
	ds_read_b128 v[144:147], v42 offset:17472
	ds_read_b128 v[148:151], v42 offset:17536
	ds_read_b128 v[152:155], v42 offset:17600
	ds_read_b128 v[156:159], v62 offset:17408
	ds_read_b128 v[160:163], v62 offset:17472
	ds_read_b128 v[164:167], v62 offset:17536
	ds_read_b128 v[168:171], v62 offset:17600
	v_mul_f32_e32 v26, v26, v27
	v_lshlrev_b32_e32 v172, 16, v22
	v_mul_f32_e32 v172, v26, v172
	v_cvt_pk_bf16_f32 v172, v172, s0
	v_and_b32_e32 v173, 0xffff0000, v22
	v_mul_f32_e32 v173, v26, v173
	v_cvt_pk_bf16_f32 v173, v173, s0
	v_lshlrev_b32_e32 v174, 16, v23
	v_mul_f32_e32 v174, v26, v174
	v_cvt_pk_bf16_f32 v174, v174, s0
	v_and_b32_e32 v175, 0xffff0000, v23
	v_mul_f32_e32 v175, v26, v175
	v_cvt_pk_bf16_f32 v175, v175, s0
	v_lshlrev_b32_e32 v176, 16, v24
	v_mul_f32_e32 v176, v26, v176
	v_cvt_pk_bf16_f32 v176, v176, s0
	v_and_b32_e32 v177, 0xffff0000, v24
	v_mul_f32_e32 v177, v26, v177
	v_cvt_pk_bf16_f32 v177, v177, s0
	v_lshlrev_b32_e32 v178, 16, v25
	v_mul_f32_e32 v178, v26, v178
	v_cvt_pk_bf16_f32 v178, v178, s0
	v_and_b32_e32 v179, 0xffff0000, v25
	v_mul_f32_e32 v179, v26, v179
	v_cvt_pk_bf16_f32 v179, v179, s0
	v_lshlrev_b32_e32 v180, 16, v18
	v_mul_f32_e32 v180, v26, v180
	v_cvt_pk_bf16_f32 v180, v180, s0
	v_and_b32_e32 v181, 0xffff0000, v18
	v_mul_f32_e32 v181, v26, v181
	v_cvt_pk_bf16_f32 v181, v181, s0
	v_lshlrev_b32_e32 v182, 16, v19
	v_mul_f32_e32 v182, v26, v182
	v_cvt_pk_bf16_f32 v182, v182, s0
	v_and_b32_e32 v183, 0xffff0000, v19
	v_mul_f32_e32 v183, v26, v183
	v_cvt_pk_bf16_f32 v183, v183, s0
	v_lshlrev_b32_e32 v184, 16, v20
	v_mul_f32_e32 v184, v26, v184
	v_cvt_pk_bf16_f32 v184, v184, s0
	v_and_b32_e32 v185, 0xffff0000, v20
	v_mul_f32_e32 v185, v26, v185
	v_cvt_pk_bf16_f32 v185, v185, s0
	v_lshlrev_b32_e32 v186, 16, v21
	v_mul_f32_e32 v186, v26, v186
	v_cvt_pk_bf16_f32 v186, v186, s0
	v_and_b32_e32 v187, 0xffff0000, v21
	v_mul_f32_e32 v187, v26, v187
	v_cvt_pk_bf16_f32 v187, v187, s0
	v_add_u32_e32 v18, s19, v104
	v_add_u32_e32 v19, 64, v18
	v_add_u32_e32 v18, 0xffffff40, v18
	v_cndmask_b32_e32 v18, v18, v19, vcc
	v_add_u32_e32 v19, s4, v118
	v_cndmask_b32_e64 v18, v19, v18, s[36:37]
	v_add_u32_e32 v38, s5, v18
	v_mov_b64_e32 v[18:19], s[12:13]
	s_movk_i32 s4, 0xe00
	v_mad_i64_i32 v[26:27], s[4:5], v38, s4, v[18:19]
	v_lshl_add_u64 v[18:19], v[26:27], 0, s[34:35]
	v_lshl_add_u64 v[18:19], v[18:19], 0, v[72:73]
	s_lshl_b32 s4, s9, 1
	s_mov_b32 s5, s35
	global_load_dwordx4 v[30:33], v[18:19], off offset:2560
	global_load_dwordx4 v[34:37], v[18:19], off offset:2688
	global_load_dwordx4 v[22:25], v[18:19], off offset:1536
	s_nop 0
	global_load_dwordx4 v[18:21], v[18:19], off offset:1664
	v_lshl_add_u64 v[26:27], v[26:27], 0, s[4:5]
	v_lshl_add_u64 v[26:27], v[26:27], 0, v[72:73]
	global_load_dwordx4 v[26:29], v[26:27], off
	s_and_saveexec_b64 s[4:5], s[54:55]
	s_cbranch_execz .Lssd_skip_dt
	v_mov_b64_e32 v[40:41], s[24:25]
	v_mad_i64_i32 v[38:39], s[28:29], v38, s97, v[40:41]
	global_load_dword v105, v[38:39], off
	global_load_dword v106, v[38:39], off offset:96
